# in-proj epilogue: drop redundant same-wave LDS write-to-read waits (placement preserved)
# speedup vs baseline: 1.0013x; 1.0013x over previous
.LBB0_202:
	s_or_b64 exec, exec, s[54:55]
	s_lshr_b32 s13, s12, 6
	s_or_b32 s13, s13, s86
	v_lshlrev_b32_e32 v198, 3, v148
	s_lshl_b32 s23, s13, 8
	v_cmp_gt_i32_e32 vcc, s22, v152
	v_lshl_add_u64 v[156:157], s[6:7], 0, v[198:199]
	v_or_b32_e32 v144, s23, v167
	v_cndmask_b32_e32 v154, 1.0, v249, vcc
	v_lshlrev_b32_e32 v151, 2, v148
	v_and_b32_e32 v161, 64, v149
	v_mad_i64_i32 v[164:165], s[54:55], v150, s62, v[156:157]
	v_ashrrev_i32_e32 v145, 31, v144
	v_ashrrev_i32_e32 v153, 31, v152
	v_pk_mul_f32 v[146:147], v[154:155], v[60:61] op_sel_hi:[0,1]
	v_pk_mul_f32 v[148:149], v[154:155], v[62:63] op_sel_hi:[0,1]
	v_lshlrev_b64 v[162:163], 9, v[144:145]
	v_lshl_add_u64 v[144:145], v[152:153], 1, v[164:165]
	v_cvt_pk_bf16_f32 v146, v146, v147
	v_cvt_pk_bf16_f32 v147, v148, v149
	ds_write_b64 v200, v[146:147]
	v_pk_mul_f32 v[146:147], v[154:155], v[52:53] op_sel_hi:[0,1]
	v_pk_mul_f32 v[148:149], v[154:155], v[54:55] op_sel_hi:[0,1]
	v_cvt_pk_bf16_f32 v146, v146, v147
	v_cvt_pk_bf16_f32 v147, v148, v149
	ds_write_b64 v200, v[146:147] offset:32
	v_pk_mul_f32 v[146:147], v[154:155], v[56:57] op_sel_hi:[0,1]
	v_pk_mul_f32 v[148:149], v[154:155], v[58:59] op_sel_hi:[0,1]
	v_cvt_pk_bf16_f32 v146, v146, v147
	v_cvt_pk_bf16_f32 v147, v148, v149
	ds_write_b64 v200, v[146:147] offset:64
	v_pk_mul_f32 v[146:147], v[154:155], v[48:49] op_sel_hi:[0,1]
	v_pk_mul_f32 v[148:149], v[154:155], v[50:51] op_sel_hi:[0,1]
	v_cvt_pk_bf16_f32 v146, v146, v147
	v_cvt_pk_bf16_f32 v147, v148, v149
	ds_write_b64 v200, v[146:147] offset:96
	s_nop 0
	ds_read_b128 v[204:207], v201
	ds_read_b128 v[208:211], v201 offset:1152
	v_lshl_add_u64 v[212:213], v[144:145], 0, v[202:203]
	v_lshl_add_u64 v[214:215], v[212:213], 0, s[100:101]
	s_waitcnt lgkmcnt(0)
	global_store_dwordx4 v[212:213], v[204:207], off sc1
	global_store_dwordx4 v[214:215], v[208:211], off sc1
	v_and_b32_e32 v144, 0xffffff00, v152
	v_cmp_eq_u32_e32 vcc, s22, v144
	s_xor_b64 s[54:55], s[52:53], -1
	s_and_b64 s[92:93], s[54:55], vcc
	v_and_b32_e32 v168, 0x280, v152
	v_lshlrev_b32_e32 v150, 2, v161
	v_lshlrev_b32_e32 v148, 2, v151
	s_and_saveexec_b64 s[94:95], s[92:93]
	s_cbranch_execz .LBB0_204
	v_cmp_eq_u32_e32 vcc, s18, v168
	v_mov_b32_e32 v151, v199
	v_mov_b32_e32 v149, v199
	v_cndmask_b32_e32 v198, 0, v250, vcc
	v_lshl_add_u64 v[144:145], s[34:35], 0, v[198:199]
	v_lshl_add_u64 v[144:145], v[144:145], 0, v[162:163]
	v_lshl_add_u64 v[144:145], v[144:145], 0, v[150:151]
	v_lshl_add_u64 v[144:145], v[144:145], 0, v[148:149]
	ds_write_b128 v216, v[60:63]
	ds_write_b128 v216, v[52:55] offset:64
	ds_write_b128 v216, v[56:59] offset:128
	ds_write_b128 v216, v[48:51] offset:192
	ds_read_b128 v[220:223], v217
	ds_read_b128 v[224:227], v217 offset:1088
	ds_read_b128 v[228:231], v217 offset:2176
	ds_read_b128 v[232:235], v217 offset:3264
	v_lshl_add_u64 v[242:243], v[144:145], 0, v[238:239]
	v_lshl_add_u64 v[218:219], v[144:145], 0, v[236:237]
	s_waitcnt lgkmcnt(0)
	global_store_dwordx4 v[218:219], v[220:223], off
	global_store_dwordx4 v[218:219], v[224:227], off offset:2048
	global_store_dwordx4 v[242:243], v[228:231], off
	global_store_dwordx4 v[242:243], v[232:235], off offset:2048

.LBB0_206:
	s_or_b64 exec, exec, s[52:53]
	v_cmp_gt_i32_e32 vcc, s22, v137
	s_ashr_i32 s89, s88, 31
	v_ashrrev_i32_e32 v159, 31, v158
	v_cndmask_b32_e32 v136, 1.0, v249, vcc
	v_lshl_add_u64 v[138:139], v[158:159], 0, s[88:89]
	v_lshl_add_u64 v[158:159], v[138:139], 1, v[164:165]
	v_pk_mul_f32 v[160:161], v[136:137], v[144:145] op_sel_hi:[0,1]
	v_pk_mul_f32 v[164:165], v[136:137], v[146:147] op_sel_hi:[0,1]
	v_cvt_pk_bf16_f32 v160, v160, v161
	v_cvt_pk_bf16_f32 v161, v164, v165
	ds_write_b64 v200, v[160:161]
	v_pk_mul_f32 v[160:161], v[136:137], v[140:141] op_sel_hi:[0,1]
	v_pk_mul_f32 v[164:165], v[136:137], v[142:143] op_sel_hi:[0,1]
	v_cvt_pk_bf16_f32 v160, v160, v161
	v_cvt_pk_bf16_f32 v161, v164, v165
	ds_write_b64 v200, v[160:161] offset:32
	v_pk_mul_f32 v[160:161], v[136:137], v[132:133] op_sel_hi:[0,1]
	v_pk_mul_f32 v[164:165], v[136:137], v[134:135] op_sel_hi:[0,1]
	v_cvt_pk_bf16_f32 v160, v160, v161
	v_cvt_pk_bf16_f32 v161, v164, v165
	ds_write_b64 v200, v[160:161] offset:64
	v_pk_mul_f32 v[160:161], v[136:137], v[128:129] op_sel_hi:[0,1]
	v_pk_mul_f32 v[164:165], v[136:137], v[130:131] op_sel_hi:[0,1]
	v_and_b32_e32 v149, 0xffffff00, v137
	v_cvt_pk_bf16_f32 v160, v160, v161
	v_cvt_pk_bf16_f32 v161, v164, v165
	v_cmp_eq_u32_e32 vcc, s22, v149
	ds_write_b64 v200, v[160:161] offset:96
	s_nop 0
	ds_read_b128 v[204:207], v201
	ds_read_b128 v[208:211], v201 offset:1152
	v_lshl_add_u64 v[212:213], v[158:159], 0, v[202:203]
	v_lshl_add_u64 v[214:215], v[212:213], 0, s[100:101]
	s_waitcnt lgkmcnt(0)
	global_store_dwordx4 v[212:213], v[204:207], off offset:256 sc1
	global_store_dwordx4 v[214:215], v[208:211], off offset:256 sc1
	s_and_b64 s[88:89], s[54:55], vcc
	v_and_b32_e32 v158, 0x280, v137
	s_and_saveexec_b64 s[52:53], s[88:89]
	s_cbranch_execz .LBB0_208
	v_cmp_eq_u32_e32 vcc, s18, v158
	v_mov_b32_e32 v151, v199
	v_mov_b32_e32 v149, v199
	v_cndmask_b32_e32 v198, 0, v250, vcc
	v_lshl_add_u64 v[160:161], s[34:35], 0, v[198:199]
	v_lshl_add_u64 v[160:161], v[160:161], 0, v[162:163]
	v_lshl_add_u64 v[160:161], v[160:161], 0, v[150:151]
	v_lshl_add_u64 v[160:161], v[160:161], 0, v[148:149]
	ds_write_b128 v216, v[144:147]
	ds_write_b128 v216, v[140:143] offset:64
	ds_write_b128 v216, v[132:135] offset:128
	ds_write_b128 v216, v[128:131] offset:192
	ds_read_b128 v[220:223], v217
	ds_read_b128 v[224:227], v217 offset:1088
	ds_read_b128 v[228:231], v217 offset:2176
	ds_read_b128 v[232:235], v217 offset:3264
	v_lshl_add_u64 v[242:243], v[160:161], 0, v[238:239]
	v_lshl_add_u64 v[218:219], v[160:161], 0, v[236:237]
	s_waitcnt lgkmcnt(0)
	global_store_dwordx4 v[218:219], v[220:223], off
	global_store_dwordx4 v[218:219], v[224:227], off offset:2048
	global_store_dwordx4 v[242:243], v[228:231], off
	global_store_dwordx4 v[242:243], v[232:235], off offset:2048

.LBB0_210:
	s_or_b64 exec, exec, s[52:53]
	v_mov_b32_e32 v155, v154
	v_mad_i64_i32 v[126:127], s[52:53], v137, s62, v[156:157]
	v_pk_mul_f32 v[142:143], v[154:155], v[128:129]
	v_pk_mul_f32 v[144:145], v[154:155], v[130:131]
	v_lshl_add_u64 v[140:141], v[152:153], 1, v[126:127]
	v_cvt_pk_bf16_f32 v142, v142, v143
	v_cvt_pk_bf16_f32 v143, v144, v145
	ds_write_b64 v200, v[142:143]
	v_pk_mul_f32 v[142:143], v[154:155], v[120:121]
	v_pk_mul_f32 v[144:145], v[154:155], v[122:123]
	v_cvt_pk_bf16_f32 v142, v142, v143
	v_cvt_pk_bf16_f32 v143, v144, v145
	ds_write_b64 v200, v[142:143] offset:32
	v_pk_mul_f32 v[142:143], v[154:155], v[116:117]
	v_pk_mul_f32 v[144:145], v[154:155], v[118:119]
	v_or_b32_e32 v124, s23, v133
	v_cvt_pk_bf16_f32 v142, v142, v143
	v_cvt_pk_bf16_f32 v143, v144, v145
	v_ashrrev_i32_e32 v125, 31, v124
	ds_write_b64 v200, v[142:143] offset:64
	v_pk_mul_f32 v[142:143], v[154:155], v[112:113]
	v_pk_mul_f32 v[144:145], v[154:155], v[114:115]
	v_lshlrev_b64 v[124:125], 9, v[124:125]
	v_cvt_pk_bf16_f32 v142, v142, v143
	v_cvt_pk_bf16_f32 v143, v144, v145
	ds_write_b64 v200, v[142:143] offset:96
	s_nop 0
	ds_read_b128 v[204:207], v201
	ds_read_b128 v[208:211], v201 offset:1152
	v_lshl_add_u64 v[212:213], v[140:141], 0, v[202:203]
	v_lshl_add_u64 v[214:215], v[212:213], 0, s[100:101]
	s_waitcnt lgkmcnt(0)
	global_store_dwordx4 v[212:213], v[204:207], off sc1
	global_store_dwordx4 v[214:215], v[208:211], off sc1
	s_and_saveexec_b64 s[52:53], s[92:93]
	s_cbranch_execz .LBB0_212
	v_cmp_eq_u32_e32 vcc, s18, v168
	v_mov_b32_e32 v151, v199
	v_mov_b32_e32 v149, v199
	v_cndmask_b32_e32 v198, 0, v250, vcc
	v_lshl_add_u64 v[140:141], s[34:35], 0, v[198:199]
	v_lshl_add_u64 v[140:141], v[140:141], 0, v[124:125]
	v_lshl_add_u64 v[140:141], v[140:141], 0, v[150:151]
	v_lshl_add_u64 v[140:141], v[140:141], 0, v[148:149]
	ds_write_b128 v216, v[128:131]
	ds_write_b128 v216, v[120:123] offset:64
	ds_write_b128 v216, v[116:119] offset:128
	ds_write_b128 v216, v[112:115] offset:192
	ds_read_b128 v[220:223], v217
	ds_read_b128 v[224:227], v217 offset:1088
	ds_read_b128 v[228:231], v217 offset:2176
	ds_read_b128 v[232:235], v217 offset:3264
	v_lshl_add_u64 v[242:243], v[140:141], 0, v[238:239]
	v_lshl_add_u64 v[218:219], v[140:141], 0, v[236:237]
	s_waitcnt lgkmcnt(0)
	global_store_dwordx4 v[218:219], v[220:223], off
	global_store_dwordx4 v[218:219], v[224:227], off offset:2048
	global_store_dwordx4 v[242:243], v[228:231], off
	global_store_dwordx4 v[242:243], v[232:235], off offset:2048

.LBB0_214:
	s_or_b64 exec, exec, s[52:53]
	v_mov_b32_e32 v137, v136
	v_pk_mul_f32 v[110:111], v[136:137], v[112:113]
	v_pk_mul_f32 v[116:117], v[136:137], v[114:115]
	v_lshl_add_u64 v[108:109], v[138:139], 1, v[126:127]
	v_cvt_pk_bf16_f32 v110, v110, v111
	v_cvt_pk_bf16_f32 v111, v116, v117
	ds_write_b64 v200, v[110:111]
	v_pk_mul_f32 v[110:111], v[136:137], v[104:105]
	v_pk_mul_f32 v[116:117], v[136:137], v[106:107]
	v_cvt_pk_bf16_f32 v110, v110, v111
	v_cvt_pk_bf16_f32 v111, v116, v117
	ds_write_b64 v200, v[110:111] offset:32
	v_pk_mul_f32 v[110:111], v[136:137], v[100:101]
	v_pk_mul_f32 v[116:117], v[136:137], v[102:103]
	v_cvt_pk_bf16_f32 v110, v110, v111
	v_cvt_pk_bf16_f32 v111, v116, v117
	ds_write_b64 v200, v[110:111] offset:64
	v_pk_mul_f32 v[110:111], v[136:137], v[96:97]
	v_pk_mul_f32 v[116:117], v[136:137], v[98:99]
	v_cvt_pk_bf16_f32 v110, v110, v111
	v_cvt_pk_bf16_f32 v111, v116, v117
	ds_write_b64 v200, v[110:111] offset:96
	s_nop 0
	ds_read_b128 v[204:207], v201
	ds_read_b128 v[208:211], v201 offset:1152
	v_lshl_add_u64 v[212:213], v[108:109], 0, v[202:203]
	v_lshl_add_u64 v[214:215], v[212:213], 0, s[100:101]
	s_waitcnt lgkmcnt(0)
	global_store_dwordx4 v[212:213], v[204:207], off offset:256 sc1
	global_store_dwordx4 v[214:215], v[208:211], off offset:256 sc1
	s_and_saveexec_b64 s[52:53], s[88:89]
	s_cbranch_execz .LBB0_216
	v_cmp_eq_u32_e32 vcc, s18, v158
	v_mov_b32_e32 v151, v199
	v_mov_b32_e32 v149, v199
	v_cndmask_b32_e32 v198, 0, v250, vcc
	v_lshl_add_u64 v[108:109], s[34:35], 0, v[198:199]
	v_lshl_add_u64 v[108:109], v[108:109], 0, v[124:125]
	v_lshl_add_u64 v[108:109], v[108:109], 0, v[150:151]
	v_lshl_add_u64 v[108:109], v[108:109], 0, v[148:149]
	ds_write_b128 v216, v[112:115]
	ds_write_b128 v216, v[104:107] offset:64
	ds_write_b128 v216, v[100:103] offset:128
	ds_write_b128 v216, v[96:99] offset:192
	ds_read_b128 v[220:223], v217
	ds_read_b128 v[224:227], v217 offset:1088
	ds_read_b128 v[228:231], v217 offset:2176
	ds_read_b128 v[232:235], v217 offset:3264
	v_lshl_add_u64 v[242:243], v[108:109], 0, v[238:239]
	v_lshl_add_u64 v[218:219], v[108:109], 0, v[236:237]
	s_waitcnt lgkmcnt(0)
	global_store_dwordx4 v[218:219], v[220:223], off
	global_store_dwordx4 v[218:219], v[224:227], off offset:2048
	global_store_dwordx4 v[242:243], v[228:231], off
	global_store_dwordx4 v[242:243], v[232:235], off offset:2048

.LBB0_218:
	s_or_b64 exec, exec, s[52:53]
	v_mad_i64_i32 v[94:95], s[52:53], v103, s62, v[156:157]
	v_pk_mul_f32 v[106:107], v[154:155], v[96:97]
	v_pk_mul_f32 v[108:109], v[154:155], v[98:99]
	v_lshl_add_u64 v[104:105], v[152:153], 1, v[94:95]
	v_cvt_pk_bf16_f32 v106, v106, v107
	v_cvt_pk_bf16_f32 v107, v108, v109
	ds_write_b64 v200, v[106:107]
	v_pk_mul_f32 v[106:107], v[154:155], v[88:89]
	v_pk_mul_f32 v[108:109], v[154:155], v[90:91]
	v_cvt_pk_bf16_f32 v106, v106, v107
	v_cvt_pk_bf16_f32 v107, v108, v109
	ds_write_b64 v200, v[106:107] offset:32
	v_pk_mul_f32 v[106:107], v[154:155], v[84:85]
	v_pk_mul_f32 v[108:109], v[154:155], v[86:87]
	v_or_b32_e32 v92, s23, v101
	v_cvt_pk_bf16_f32 v106, v106, v107
	v_cvt_pk_bf16_f32 v107, v108, v109
	v_ashrrev_i32_e32 v93, 31, v92
	ds_write_b64 v200, v[106:107] offset:64
	v_pk_mul_f32 v[106:107], v[154:155], v[80:81]
	v_pk_mul_f32 v[108:109], v[154:155], v[82:83]
	v_lshlrev_b64 v[92:93], 9, v[92:93]
	v_cvt_pk_bf16_f32 v106, v106, v107
	v_cvt_pk_bf16_f32 v107, v108, v109
	ds_write_b64 v200, v[106:107] offset:96
	s_nop 0
	ds_read_b128 v[204:207], v201
	ds_read_b128 v[208:211], v201 offset:1152
	v_lshl_add_u64 v[212:213], v[104:105], 0, v[202:203]
	v_lshl_add_u64 v[214:215], v[212:213], 0, s[100:101]
	s_waitcnt lgkmcnt(0)
	global_store_dwordx4 v[212:213], v[204:207], off sc1
	global_store_dwordx4 v[214:215], v[208:211], off sc1
	s_and_saveexec_b64 s[52:53], s[92:93]
	s_cbranch_execz .LBB0_220
	v_cmp_eq_u32_e32 vcc, s18, v168
	v_mov_b32_e32 v151, v199
	v_mov_b32_e32 v149, v199
	v_cndmask_b32_e32 v198, 0, v250, vcc
	v_lshl_add_u64 v[104:105], s[34:35], 0, v[198:199]
	v_lshl_add_u64 v[104:105], v[104:105], 0, v[92:93]
	v_lshl_add_u64 v[104:105], v[104:105], 0, v[150:151]
	v_lshl_add_u64 v[104:105], v[104:105], 0, v[148:149]
	ds_write_b128 v216, v[96:99]
	ds_write_b128 v216, v[88:91] offset:64
	ds_write_b128 v216, v[84:87] offset:128
	ds_write_b128 v216, v[80:83] offset:192
	ds_read_b128 v[220:223], v217
	ds_read_b128 v[224:227], v217 offset:1088
	ds_read_b128 v[228:231], v217 offset:2176
	ds_read_b128 v[232:235], v217 offset:3264
	v_lshl_add_u64 v[242:243], v[104:105], 0, v[238:239]
	v_lshl_add_u64 v[218:219], v[104:105], 0, v[236:237]
	s_waitcnt lgkmcnt(0)
	global_store_dwordx4 v[218:219], v[220:223], off
	global_store_dwordx4 v[218:219], v[224:227], off offset:2048
	global_store_dwordx4 v[242:243], v[228:231], off
	global_store_dwordx4 v[242:243], v[232:235], off offset:2048

.LBB0_222:
	s_or_b64 exec, exec, s[52:53]
	v_pk_mul_f32 v[78:79], v[136:137], v[80:81]
	v_pk_mul_f32 v[84:85], v[136:137], v[82:83]
	v_lshl_add_u64 v[76:77], v[138:139], 1, v[94:95]
	v_cvt_pk_bf16_f32 v78, v78, v79
	v_cvt_pk_bf16_f32 v79, v84, v85
	ds_write_b64 v200, v[78:79]
	v_pk_mul_f32 v[78:79], v[136:137], v[72:73]
	v_pk_mul_f32 v[84:85], v[136:137], v[74:75]
	v_cvt_pk_bf16_f32 v78, v78, v79
	v_cvt_pk_bf16_f32 v79, v84, v85
	ds_write_b64 v200, v[78:79] offset:32
	v_pk_mul_f32 v[78:79], v[136:137], v[68:69]
	v_pk_mul_f32 v[84:85], v[136:137], v[70:71]
	v_cvt_pk_bf16_f32 v78, v78, v79
	v_cvt_pk_bf16_f32 v79, v84, v85
	ds_write_b64 v200, v[78:79] offset:64
	v_pk_mul_f32 v[78:79], v[136:137], v[64:65]
	v_pk_mul_f32 v[84:85], v[136:137], v[66:67]
	v_cvt_pk_bf16_f32 v78, v78, v79
	v_cvt_pk_bf16_f32 v79, v84, v85
	ds_write_b64 v200, v[78:79] offset:96
	s_nop 0
	ds_read_b128 v[204:207], v201
	ds_read_b128 v[208:211], v201 offset:1152
	v_lshl_add_u64 v[212:213], v[76:77], 0, v[202:203]
	v_lshl_add_u64 v[214:215], v[212:213], 0, s[100:101]
	s_waitcnt lgkmcnt(0)
	global_store_dwordx4 v[212:213], v[204:207], off offset:256 sc1
	global_store_dwordx4 v[214:215], v[208:211], off offset:256 sc1
	s_and_saveexec_b64 s[52:53], s[88:89]
	s_cbranch_execz .LBB0_224
	v_cmp_eq_u32_e32 vcc, s18, v158
	v_mov_b32_e32 v151, v199
	v_mov_b32_e32 v149, v199
	v_cndmask_b32_e32 v198, 0, v250, vcc
	v_lshl_add_u64 v[76:77], s[34:35], 0, v[198:199]
	v_lshl_add_u64 v[76:77], v[76:77], 0, v[92:93]
	v_lshl_add_u64 v[76:77], v[76:77], 0, v[150:151]
	v_lshl_add_u64 v[76:77], v[76:77], 0, v[148:149]
	ds_write_b128 v216, v[80:83]
	ds_write_b128 v216, v[72:75] offset:64
	ds_write_b128 v216, v[68:71] offset:128
	ds_write_b128 v216, v[64:67] offset:192
	ds_read_b128 v[220:223], v217
	ds_read_b128 v[224:227], v217 offset:1088
	ds_read_b128 v[228:231], v217 offset:2176
	ds_read_b128 v[232:235], v217 offset:3264
	v_lshl_add_u64 v[242:243], v[76:77], 0, v[238:239]
	v_lshl_add_u64 v[218:219], v[76:77], 0, v[236:237]
	s_waitcnt lgkmcnt(0)
	global_store_dwordx4 v[218:219], v[220:223], off
	global_store_dwordx4 v[218:219], v[224:227], off offset:2048
	global_store_dwordx4 v[242:243], v[228:231], off
	global_store_dwordx4 v[242:243], v[232:235], off offset:2048

.LBB0_226:
	s_or_b64 exec, exec, s[12:13]
	v_mad_i64_i32 v[30:31], s[12:13], v66, s62, v[156:157]
	v_pk_mul_f32 v[40:41], v[154:155], v[32:33]
	v_pk_mul_f32 v[42:43], v[154:155], v[34:35]
	v_lshl_add_u64 v[38:39], v[152:153], 1, v[30:31]
	v_cvt_pk_bf16_f32 v40, v40, v41
	v_cvt_pk_bf16_f32 v41, v42, v43
	ds_write_b64 v200, v[40:41]
	v_pk_mul_f32 v[40:41], v[154:155], v[24:25]
	v_pk_mul_f32 v[42:43], v[154:155], v[26:27]
	v_cvt_pk_bf16_f32 v40, v40, v41
	v_cvt_pk_bf16_f32 v41, v42, v43
	ds_write_b64 v200, v[40:41] offset:32
	v_pk_mul_f32 v[40:41], v[154:155], v[20:21]
	v_pk_mul_f32 v[42:43], v[154:155], v[22:23]
	v_or_b32_e32 v28, s23, v65
	v_cvt_pk_bf16_f32 v40, v40, v41
	v_cvt_pk_bf16_f32 v41, v42, v43
	v_ashrrev_i32_e32 v29, 31, v28
	ds_write_b64 v200, v[40:41] offset:64
	v_pk_mul_f32 v[40:41], v[154:155], v[16:17]
	v_pk_mul_f32 v[42:43], v[154:155], v[18:19]
	v_lshlrev_b64 v[28:29], 9, v[28:29]
	v_cvt_pk_bf16_f32 v40, v40, v41
	v_cvt_pk_bf16_f32 v41, v42, v43
	ds_write_b64 v200, v[40:41] offset:96
	s_nop 0
	ds_read_b128 v[204:207], v201
	ds_read_b128 v[208:211], v201 offset:1152
	v_lshl_add_u64 v[212:213], v[38:39], 0, v[202:203]
	v_lshl_add_u64 v[214:215], v[212:213], 0, s[100:101]
	s_waitcnt lgkmcnt(0)
	global_store_dwordx4 v[212:213], v[204:207], off sc1
	global_store_dwordx4 v[214:215], v[208:211], off sc1
	s_and_saveexec_b64 s[12:13], s[92:93]
	s_cbranch_execz .LBB0_228
	v_cmp_eq_u32_e32 vcc, s18, v168
	v_mov_b32_e32 v151, v199
	v_mov_b32_e32 v149, v199
	v_cndmask_b32_e32 v198, 0, v250, vcc
	v_lshl_add_u64 v[38:39], s[34:35], 0, v[198:199]
	v_lshl_add_u64 v[38:39], v[38:39], 0, v[28:29]
	v_lshl_add_u64 v[38:39], v[38:39], 0, v[150:151]
	v_lshl_add_u64 v[38:39], v[38:39], 0, v[148:149]
	ds_write_b128 v216, v[32:35]
	ds_write_b128 v216, v[24:27] offset:64
	ds_write_b128 v216, v[20:23] offset:128
	ds_write_b128 v216, v[16:19] offset:192
	ds_read_b128 v[220:223], v217
	ds_read_b128 v[224:227], v217 offset:1088
	ds_read_b128 v[228:231], v217 offset:2176
	ds_read_b128 v[232:235], v217 offset:3264
	v_lshl_add_u64 v[242:243], v[38:39], 0, v[238:239]
	v_lshl_add_u64 v[218:219], v[38:39], 0, v[236:237]
	s_waitcnt lgkmcnt(0)
	global_store_dwordx4 v[218:219], v[220:223], off
	global_store_dwordx4 v[218:219], v[224:227], off offset:2048
	global_store_dwordx4 v[242:243], v[228:231], off
	global_store_dwordx4 v[242:243], v[232:235], off offset:2048

.LBB0_230:
	s_or_b64 exec, exec, s[12:13]
	v_pk_mul_f32 v[14:15], v[136:137], v[16:17]
	v_pk_mul_f32 v[20:21], v[136:137], v[18:19]
	v_lshl_add_u64 v[12:13], v[138:139], 1, v[30:31]
	v_cvt_pk_bf16_f32 v14, v14, v15
	v_cvt_pk_bf16_f32 v15, v20, v21
	ds_write_b64 v200, v[14:15]
	v_pk_mul_f32 v[14:15], v[136:137], v[8:9]
	v_pk_mul_f32 v[20:21], v[136:137], v[10:11]
	v_cvt_pk_bf16_f32 v14, v14, v15
	v_cvt_pk_bf16_f32 v15, v20, v21
	ds_write_b64 v200, v[14:15] offset:32
	v_pk_mul_f32 v[14:15], v[136:137], v[4:5]
	v_pk_mul_f32 v[20:21], v[136:137], v[6:7]
	v_cvt_pk_bf16_f32 v14, v14, v15
	v_cvt_pk_bf16_f32 v15, v20, v21
	ds_write_b64 v200, v[14:15] offset:64
	v_pk_mul_f32 v[14:15], v[136:137], v[0:1]
	v_pk_mul_f32 v[20:21], v[136:137], v[2:3]
	v_cvt_pk_bf16_f32 v14, v14, v15
	v_cvt_pk_bf16_f32 v15, v20, v21
	ds_write_b64 v200, v[14:15] offset:96
	s_nop 0
	ds_read_b128 v[204:207], v201
	ds_read_b128 v[208:211], v201 offset:1152
	v_lshl_add_u64 v[212:213], v[12:13], 0, v[202:203]
	v_lshl_add_u64 v[214:215], v[212:213], 0, s[100:101]
	s_waitcnt lgkmcnt(0)
	global_store_dwordx4 v[212:213], v[204:207], off offset:256 sc1
	global_store_dwordx4 v[214:215], v[208:211], off offset:256 sc1
	s_and_saveexec_b64 s[12:13], s[88:89]
	s_cbranch_execz .LBB0_189
	v_cmp_eq_u32_e32 vcc, s18, v158
	v_mov_b32_e32 v151, v199
	v_mov_b32_e32 v149, v199
	v_cndmask_b32_e32 v198, 0, v250, vcc
	v_lshl_add_u64 v[12:13], s[34:35], 0, v[198:199]
	v_lshl_add_u64 v[12:13], v[12:13], 0, v[28:29]
	v_lshl_add_u64 v[12:13], v[12:13], 0, v[150:151]
	v_lshl_add_u64 v[12:13], v[12:13], 0, v[148:149]
	ds_write_b128 v216, v[16:19]
	ds_write_b128 v216, v[8:11] offset:64
	ds_write_b128 v216, v[4:7] offset:128
	ds_write_b128 v216, v[0:3] offset:192
	ds_read_b128 v[220:223], v217
	ds_read_b128 v[224:227], v217 offset:1088
	ds_read_b128 v[228:231], v217 offset:2176
	ds_read_b128 v[232:235], v217 offset:3264
	v_lshl_add_u64 v[242:243], v[12:13], 0, v[238:239]
	v_lshl_add_u64 v[218:219], v[12:13], 0, v[236:237]
	s_waitcnt lgkmcnt(0)
	global_store_dwordx4 v[218:219], v[220:223], off
	global_store_dwordx4 v[218:219], v[224:227], off offset:2048
	global_store_dwordx4 v[242:243], v[228:231], off
	global_store_dwordx4 v[242:243], v[232:235], off offset:2048
	s_branch .LBB0_189
